# attention item prologue: first rope table load group issued ahead of the Q loads (saddr form into spare registers)
# speedup vs baseline: 1.0058x; 1.0058x over previous
.LBB0_708:
	v_ashrrev_i32_e32 v160, 6, v84
	v_and_b32_e32 v85, 31, v84
	s_lshl_b64 s[6:7], s[48:49], 2
	v_lshlrev_b32_e32 v0, 5, v160
	s_add_u32 s20, s1, s6
	v_add3_u32 v144, v85, s27, v0
	s_addc_u32 s21, s0, s7
	v_ashrrev_i32_e32 v145, 31, v144
	s_ashr_i32 s5, s4, 31
	v_lshl_add_u64 v[0:1], v[144:145], 3, s[4:5]
	v_mov_b64_e32 v[2:3], s[30:31]
	s_movk_i32 s6, 0x180
	v_bfe_u32 v147, v84, 5, 1
	v_mad_u64_u32 v[2:3], s[0:1], v0, s6, v[2:3]
	v_mad_i32_i24 v3, v1, s6, v3
	v_lshlrev_b32_e32 v164, 4, v147
	v_lshl_add_u64 v[0:1], v[2:3], 0, v[164:165]
	s_mov_b32 s0, 0xb078000
	v_add_co_u32_e32 v2, vcc, s0, v0
	s_mov_b64 s[0:1], 0xb078000
	s_nop 0
	v_addc_co_u32_e32 v3, vcc, 0, v1, vcc
	s_add_u32 s100, s14, 0x1fa7c000
	s_addc_u32 s101, s15, 0
	v_lshlrev_b32_e32 v252, 1, v144
	v_and_b32_e32 v252, 0x1f80, v252
	v_lshl_add_u32 v252, v147, 6, v252
	global_load_dwordx4 v[240:243], v252, s[100:101] offset:48
	global_load_dwordx4 v[244:247], v252, s[100:101] offset:32
	global_load_dwordx4 v[248:251], v252, s[100:101] offset:16
	global_load_dwordx4 v[252:255], v252, s[100:101]
	global_load_dwordx4 v[14:17], v[2:3], off
	v_lshl_add_u64 v[12:13], v[0:1], 0, s[0:1]
	global_load_dwordx4 v[18:21], v[12:13], off offset:32
	global_load_dwordx4 v[22:25], v[12:13], off offset:64
	global_load_dwordx4 v[26:29], v[12:13], off offset:96
	global_load_dwordx4 v[30:33], v[12:13], off offset:128
	global_load_dwordx4 v[34:37], v[12:13], off offset:160
	global_load_dwordx4 v[38:41], v[12:13], off offset:192
	global_load_dwordx4 v[0:3], v[12:13], off offset:224
	global_load_dwordx4 v[4:7], v[12:13], off offset:256
	global_load_dwordx4 v[8:11], v[12:13], off offset:288
	global_load_dwordx4 v[64:67], v[12:13], off offset:352
	global_load_dwordx4 v[68:71], v[12:13], off offset:320
	v_lshlrev_b32_e32 v108, 5, v147
	global_load_dwordx4 v[76:79], v108, s[20:21] offset:656
	global_load_dwordx4 v[80:83], v108, s[20:21] offset:640
	global_load_dwordx4 v[88:91], v108, s[20:21] offset:720
	global_load_dwordx4 v[92:95], v108, s[20:21] offset:704
	v_lshlrev_b32_e32 v146, 3, v147
	s_waitcnt vmcnt(14)
	v_lshlrev_b32_e32 v223, 16, v18
	v_and_b32_e32 v221, 0xffff0000, v18
	v_lshlrev_b32_e32 v219, 16, v19
	v_and_b32_e32 v220, 0xffff0000, v14
	v_lshlrev_b32_e32 v222, 16, v14
	v_mul_f32_e32 v102, v220, v220
	v_lshlrev_b32_e32 v218, 16, v15
	v_fmac_f32_e32 v102, v222, v222
	v_and_b32_e32 v216, 0xffff0000, v15
	v_fmac_f32_e32 v102, v218, v218
	v_lshlrev_b32_e32 v214, 16, v16
	v_fmac_f32_e32 v102, v216, v216
	v_and_b32_e32 v212, 0xffff0000, v16
	v_fmac_f32_e32 v102, v214, v214
	v_lshlrev_b32_e32 v210, 16, v17
	v_fmac_f32_e32 v102, v212, v212
	v_and_b32_e32 v208, 0xffff0000, v17
	v_fmac_f32_e32 v102, v210, v210
	v_fmac_f32_e32 v102, v208, v208
	v_fmac_f32_e32 v102, v223, v223
	v_fmac_f32_e32 v102, v221, v221
	v_and_b32_e32 v217, 0xffff0000, v19
	v_fmac_f32_e32 v102, v219, v219
	v_lshlrev_b32_e32 v215, 16, v20
	v_fmac_f32_e32 v102, v217, v217
	v_and_b32_e32 v213, 0xffff0000, v20
	v_fmac_f32_e32 v102, v215, v215
	v_lshlrev_b32_e32 v211, 16, v21
	v_fmac_f32_e32 v102, v213, v213
	v_and_b32_e32 v209, 0xffff0000, v21
	v_fmac_f32_e32 v102, v211, v211
	s_waitcnt vmcnt(13)
	v_lshlrev_b32_e32 v207, 16, v22
	v_fmac_f32_e32 v102, v209, v209
	v_and_b32_e32 v206, 0xffff0000, v22
	v_fmac_f32_e32 v102, v207, v207
	v_lshlrev_b32_e32 v205, 16, v23
	v_fmac_f32_e32 v102, v206, v206
	v_and_b32_e32 v204, 0xffff0000, v23
	v_fmac_f32_e32 v102, v205, v205
	v_lshlrev_b32_e32 v203, 16, v24
	v_fmac_f32_e32 v102, v204, v204
	v_and_b32_e32 v202, 0xffff0000, v24
	v_fmac_f32_e32 v102, v203, v203
	v_lshlrev_b32_e32 v201, 16, v25
	v_and_b32_e32 v200, 0xffff0000, v25
	s_waitcnt vmcnt(12)
	v_lshlrev_b32_e32 v199, 16, v26
	v_and_b32_e32 v198, 0xffff0000, v26
	v_lshlrev_b32_e32 v187, 16, v27
	v_and_b32_e32 v186, 0xffff0000, v27
	v_lshlrev_b32_e32 v185, 16, v28
	v_and_b32_e32 v184, 0xffff0000, v28
	v_lshlrev_b32_e32 v183, 16, v29
	v_and_b32_e32 v182, 0xffff0000, v29
	s_waitcnt vmcnt(11)
	v_lshlrev_b32_e32 v181, 16, v30
	v_and_b32_e32 v180, 0xffff0000, v30
	v_lshlrev_b32_e32 v179, 16, v31
	v_and_b32_e32 v178, 0xffff0000, v31
	v_lshlrev_b32_e32 v177, 16, v32
	v_and_b32_e32 v176, 0xffff0000, v32
	v_lshlrev_b32_e32 v175, 16, v33
	v_and_b32_e32 v174, 0xffff0000, v33
	s_waitcnt vmcnt(10)
	v_lshlrev_b32_e32 v173, 16, v34
	v_and_b32_e32 v172, 0xffff0000, v34
	v_lshlrev_b32_e32 v171, 16, v35
	v_and_b32_e32 v170, 0xffff0000, v35
	v_lshlrev_b32_e32 v169, 16, v36
	v_and_b32_e32 v168, 0xffff0000, v36
	v_lshlrev_b32_e32 v167, 16, v37
	v_and_b32_e32 v166, 0xffff0000, v37
	s_waitcnt vmcnt(9)
	v_lshlrev_b32_e32 v163, 16, v38
	v_and_b32_e32 v162, 0xffff0000, v38
	v_lshlrev_b32_e32 v161, 16, v39
	v_and_b32_e32 v139, 0xffff0000, v39
	v_lshlrev_b32_e32 v138, 16, v40
	v_and_b32_e32 v137, 0xffff0000, v40
	v_lshlrev_b32_e32 v136, 16, v41
	v_and_b32_e32 v103, 0xffff0000, v41
	v_fmac_f32_e32 v102, v202, v202
	s_waitcnt vmcnt(8)
	v_lshlrev_b32_e32 v224, 16, v0
	v_and_b32_e32 v229, 0xffff0000, v0
	v_lshlrev_b32_e32 v230, 16, v1
	v_and_b32_e32 v228, 0xffff0000, v1
	v_lshlrev_b32_e32 v227, 16, v2
	v_and_b32_e32 v226, 0xffff0000, v2
	v_lshlrev_b32_e32 v225, 16, v3
	v_and_b32_e32 v231, 0xffff0000, v3
	s_waitcnt vmcnt(7)
	v_lshlrev_b32_e32 v86, 16, v4
	v_and_b32_e32 v87, 0xffff0000, v4
	v_lshlrev_b32_e32 v112, 16, v5
	v_and_b32_e32 v113, 0xffff0000, v5
	v_lshlrev_b32_e32 v114, 16, v6
	v_and_b32_e32 v115, 0xffff0000, v6
	v_lshlrev_b32_e32 v116, 16, v7
	v_and_b32_e32 v117, 0xffff0000, v7
	s_waitcnt vmcnt(6)
	v_lshlrev_b32_e32 v118, 16, v8
	v_and_b32_e32 v119, 0xffff0000, v8
	v_lshlrev_b32_e32 v120, 16, v9
	v_and_b32_e32 v121, 0xffff0000, v9
	v_lshlrev_b32_e32 v122, 16, v10
	v_and_b32_e32 v123, 0xffff0000, v10
	v_lshlrev_b32_e32 v124, 16, v11
	v_and_b32_e32 v125, 0xffff0000, v11
	global_load_dwordx4 v[56:59], v108, s[20:21] offset:16
	global_load_dwordx4 v[60:63], v108, s[20:21]
	global_load_dwordx4 v[48:51], v108, s[20:21] offset:80
	global_load_dwordx4 v[52:55], v108, s[20:21] offset:64
	global_load_dwordx4 v[40:43], v108, s[20:21] offset:144
	global_load_dwordx4 v[44:47], v108, s[20:21] offset:128
	global_load_dwordx4 v[32:35], v108, s[20:21] offset:208
	global_load_dwordx4 v[36:39], v108, s[20:21] offset:192
	global_load_dwordx4 v[24:27], v108, s[20:21] offset:272
	global_load_dwordx4 v[28:31], v108, s[20:21] offset:256
	global_load_dwordx4 v[16:19], v108, s[20:21] offset:336
	global_load_dwordx4 v[20:23], v108, s[20:21] offset:320
	global_load_dwordx4 v[8:11], v108, s[20:21] offset:400
	global_load_dwordx4 v[12:15], v108, s[20:21] offset:384
	global_load_dwordx4 v[0:3], v108, s[20:21] offset:464
	global_load_dwordx4 v[4:7], v108, s[20:21] offset:448
	v_fmac_f32_e32 v102, v201, v201
	v_fmac_f32_e32 v102, v200, v200
	v_fmac_f32_e32 v102, v199, v199
	v_fmac_f32_e32 v102, v198, v198
	v_fmac_f32_e32 v102, v187, v187
	v_fmac_f32_e32 v102, v186, v186
	v_fmac_f32_e32 v102, v185, v185
	v_fmac_f32_e32 v102, v184, v184
	v_fmac_f32_e32 v102, v183, v183
	global_load_dwordx4 v[72:75], v108, s[20:21] offset:528
	global_load_dwordx4 v[96:99], v108, s[20:21] offset:512
	global_load_dwordx4 v[104:107], v108, s[20:21] offset:592
	s_nop 0
	global_load_dwordx4 v[108:111], v108, s[20:21] offset:576
	v_fmac_f32_e32 v102, v182, v182
	v_fmac_f32_e32 v102, v181, v181
	v_fmac_f32_e32 v102, v180, v180
	v_fmac_f32_e32 v102, v179, v179
	v_fmac_f32_e32 v102, v178, v178
	v_fmac_f32_e32 v102, v177, v177
	v_fmac_f32_e32 v102, v176, v176
	v_fmac_f32_e32 v102, v175, v175
	v_fmac_f32_e32 v102, v174, v174
	v_fmac_f32_e32 v102, v173, v173
	v_fmac_f32_e32 v102, v172, v172
	v_fmac_f32_e32 v102, v171, v171
	v_fmac_f32_e32 v102, v170, v170
	v_fmac_f32_e32 v102, v169, v169
	v_fmac_f32_e32 v102, v168, v168
	v_fmac_f32_e32 v102, v167, v167
	v_fmac_f32_e32 v102, v166, v166
	v_fmac_f32_e32 v102, v163, v163
	v_fmac_f32_e32 v102, v162, v162
	v_fmac_f32_e32 v102, v161, v161
	v_fmac_f32_e32 v102, v139, v139
	v_fmac_f32_e32 v102, v138, v138
	v_fmac_f32_e32 v102, v137, v137
	v_fmac_f32_e32 v102, v136, v136
	v_fmac_f32_e32 v102, v103, v103
	v_fmac_f32_e32 v102, v224, v224
	v_fmac_f32_e32 v102, v229, v229
	v_fmac_f32_e32 v102, v230, v230
	v_fmac_f32_e32 v102, v228, v228
	v_fmac_f32_e32 v102, v227, v227
	v_fmac_f32_e32 v102, v226, v226
	v_fmac_f32_e32 v102, v225, v225
	v_fmac_f32_e32 v102, v231, v231
	v_pk_mul_f32 v[140:141], v[86:87], v[86:87]
	v_pk_mul_f32 v[132:133], v[112:113], v[112:113]
	v_add_f32_e32 v102, v140, v102
	v_add_f32_e32 v102, v141, v102
	v_add_f32_e32 v102, v132, v102
	v_pk_mul_f32 v[128:129], v[114:115], v[114:115]
	v_add_f32_e32 v102, v133, v102
	v_add_f32_e32 v102, v128, v102
	v_pk_mul_f32 v[100:101], v[116:117], v[116:117]
	v_add_f32_e32 v102, v129, v102
	v_add_f32_e32 v100, v100, v102
	v_pk_mul_f32 v[140:141], v[118:119], v[118:119]
	v_add_f32_e32 v100, v101, v100
	v_add_f32_e32 v100, v140, v100
	v_pk_mul_f32 v[134:135], v[120:121], v[120:121]
	v_add_f32_e32 v100, v141, v100
	v_add_f32_e32 v100, v134, v100
	v_pk_mul_f32 v[130:131], v[122:123], v[122:123]
	v_add_f32_e32 v100, v135, v100
	v_add_f32_e32 v100, v130, v100
	v_pk_mul_f32 v[126:127], v[124:125], v[124:125]
	v_add_f32_e32 v100, v131, v100
	v_add_f32_e32 v100, v126, v100
	v_add_f32_e32 v102, v127, v100
	s_waitcnt vmcnt(24)
	v_lshlrev_b32_e32 v127, 16, v68
	v_and_b32_e32 v129, 0xffff0000, v68
	v_fmac_f32_e32 v102, v127, v127
	v_fmac_f32_e32 v102, v129, v129
	v_lshlrev_b32_e32 v135, 16, v69
	v_and_b32_e32 v126, 0xffff0000, v64
	v_lshlrev_b32_e32 v128, 16, v64
	v_and_b32_e32 v134, 0xffff0000, v65
	v_lshlrev_b32_e32 v64, 16, v65
	v_and_b32_e32 v65, 0xffff0000, v69
	v_fmac_f32_e32 v102, v135, v135
	v_fmac_f32_e32 v102, v65, v65
	v_lshlrev_b32_e32 v151, 16, v70
	v_and_b32_e32 v153, 0xffff0000, v70
	v_fmac_f32_e32 v102, v151, v151
	v_fmac_f32_e32 v102, v153, v153
	v_lshlrev_b32_e32 v235, 16, v71
	v_mov_b32_e32 v130, v128
	v_mov_b32_e32 v131, v126
	v_and_b32_e32 v150, 0xffff0000, v66
	v_lshlrev_b32_e32 v152, 16, v66
	v_and_b32_e32 v234, 0xffff0000, v67
	v_lshlrev_b32_e32 v66, 16, v67
	v_and_b32_e32 v67, 0xffff0000, v71
	v_fmac_f32_e32 v102, v235, v235
	v_pk_mul_f32 v[100:101], v[130:131], v[130:131]
	v_fmac_f32_e32 v102, v67, v67
	v_mov_b32_e32 v68, v64
	v_mov_b32_e32 v69, v134
	v_add_f32_e32 v100, v100, v102
	v_pk_mul_f32 v[140:141], v[68:69], v[68:69]
	v_add_f32_e32 v100, v101, v100
	v_mov_b32_e32 v232, v152
	v_mov_b32_e32 v233, v150
	v_add_f32_e32 v100, v140, v100
	v_pk_mul_f32 v[148:149], v[232:233], v[232:233]
	v_add_f32_e32 v100, v141, v100
	v_mov_b32_e32 v70, v66
	v_mov_b32_e32 v71, v234
	v_add_f32_e32 v100, v148, v100
	v_pk_mul_f32 v[154:155], v[70:71], v[70:71]
	v_add_f32_e32 v100, v149, v100
	v_add_f32_e32 v100, v154, v100
	v_add_f32_e32 v100, v155, v100
	v_mov_b32_e32 v101, v100
	s_nop 1
	v_permlane32_swap_b32_e32 v100, v101
	v_add_f32_e32 v100, v100, v101
	v_fmamk_f32 v100, v100, 0x3baaaaab, v189
	v_mul_f32_e32 v101, 0x4b800000, v100
	v_cmp_gt_f32_e32 vcc, s28, v100
	s_waitcnt vmcnt(22)
	v_mov_b32_e32 v142, v82
	s_waitcnt vmcnt(20)
	v_mov_b32_e32 v82, v94
	v_cndmask_b32_e32 v100, v100, v101, vcc
	v_rsq_f32_e32 v100, v100
	v_mov_b32_e32 v132, v80
	v_mov_b32_e32 v80, v92
	v_mov_b32_e32 v133, v93
	v_mul_f32_e32 v101, 0x45800000, v100
	v_cndmask_b32_e32 v102, v100, v101, vcc
	s_waitcnt vmcnt(2)
	v_pk_mul_f32 v[96:97], v[102:103], v[96:97] op_sel_hi:[0,1]
	v_pk_mul_f32 v[72:73], v[102:103], v[72:73] op_sel_hi:[0,1]
	v_pk_mul_f32 v[100:101], v[96:97], v[86:87]
	v_pk_mul_f32 v[96:97], v[72:73], v[114:115]
	v_pk_mul_f32 v[72:73], v[102:103], v[74:75] op_sel_hi:[0,1]
	v_pk_mul_f32 v[86:87], v[102:103], v[98:99] op_sel_hi:[0,1]
	v_pk_mul_f32 v[158:159], v[72:73], v[116:117]
	s_waitcnt vmcnt(0)
	v_pk_mul_f32 v[72:73], v[102:103], v[108:109] op_sel_hi:[0,1]
	v_pk_mul_f32 v[82:83], v[102:103], v[82:83] op_sel_hi:[0,1]
	v_pk_mul_f32 v[98:99], v[86:87], v[112:113]
	v_pk_mul_f32 v[154:155], v[72:73], v[118:119]
	v_pk_mul_f32 v[72:73], v[102:103], v[110:111] op_sel_hi:[0,1]
	v_pk_mul_f32 v[86:87], v[102:103], v[106:107] op_sel_hi:[0,1]
	v_pk_mul_f32 v[110:111], v[82:83], v[64:65]
	v_pk_mul_f32 v[64:65], v[102:103], v[88:89] op_sel_hi:[0,1]
	v_mov_b32_e32 v143, v95
	v_mov_b32_e32 v140, v76
	v_mov_b32_e32 v141, v89
	v_mov_b32_e32 v76, v88
	v_pk_mul_f32 v[156:157], v[86:87], v[124:125]
	v_pk_mul_f32 v[80:81], v[102:103], v[80:81] op_sel_hi:[0,1]
	v_mov_b32_e32 v86, v78
	v_mov_b32_e32 v87, v91
	v_mov_b32_e32 v78, v90
	v_pk_mul_f32 v[88:89], v[64:65], v[232:233]
	v_pk_mul_f32 v[64:65], v[102:103], v[90:91] op_sel_hi:[0,1]
	v_pk_mul_f32 v[74:75], v[72:73], v[120:121]
	v_pk_mul_f32 v[72:73], v[102:103], v[104:105] op_sel_hi:[0,1]
	v_pk_mul_f32 v[104:105], v[102:103], v[132:133] op_sel_hi:[0,1]
	v_pk_mul_f32 v[106:107], v[102:103], v[142:143] op_sel_hi:[0,1]
	v_pk_mul_f32 v[112:113], v[102:103], v[140:141] op_sel_hi:[0,1]
	v_pk_mul_f32 v[76:77], v[102:103], v[76:77] op_sel_hi:[0,1]
	v_pk_mul_f32 v[114:115], v[102:103], v[86:87] op_sel_hi:[0,1]
	v_pk_mul_f32 v[78:79], v[102:103], v[78:79] op_sel_hi:[0,1]
	v_pk_mul_f32 v[86:87], v[102:103], v[92:93] op_sel_hi:[0,1]
	v_pk_mul_f32 v[108:109], v[80:81], v[128:129]
	v_pk_mul_f32 v[80:81], v[102:103], v[94:95] op_sel_hi:[0,1]
	v_pk_mul_f32 v[90:91], v[64:65], v[70:71]
	v_cndmask_b32_e64 v64, 0, 1, s[16:17]
	v_pk_mul_f32 v[72:73], v[72:73], v[122:123]
	v_pk_mul_f32 v[86:87], v[86:87], v[130:131]
	v_pk_mul_f32 v[140:141], v[104:105], v[126:127] op_sel:[0,1] op_sel_hi:[1,0]
	v_pk_mul_f32 v[92:93], v[80:81], v[68:69]
	v_pk_mul_f32 v[148:149], v[106:107], v[134:135] op_sel:[0,1] op_sel_hi:[1,0]
	v_pk_mul_f32 v[94:95], v[76:77], v[152:153]
	v_pk_mul_f32 v[150:151], v[112:113], v[150:151] op_sel:[0,1] op_sel_hi:[1,0]
	v_pk_mul_f32 v[142:143], v[78:79], v[66:67]
	v_cmp_ne_u32_e64 s[36:37], 1, v64
	s_andn2_b64 vcc, exec, s[16:17]
	v_pk_mul_f32 v[152:153], v[114:115], v[234:235] op_sel:[0,1] op_sel_hi:[1,0]
	s_cbranch_vccnz .LBB0_710
	v_lshlrev_b32_e32 v164, 3, v146
	v_lshl_add_u64 v[64:65], s[14:15], 0, v[164:165]
	s_mov_b64 s[0:1], 0x1fa7c000
	v_lshl_add_u64 v[76:77], v[64:65], 0, s[0:1]
	v_lshlrev_b32_e32 v64, 1, v144
	v_and_b32_e32 v164, 0x1f80, v64
	v_lshl_add_u64 v[64:65], v[76:77], 0, v[164:165]
	v_mov_b32_e32 v68, v240
	v_mov_b32_e32 v69, v241
	v_mov_b32_e32 v70, v242
	v_mov_b32_e32 v71, v243
	v_mov_b32_e32 v78, v244
	v_mov_b32_e32 v79, v245
	v_mov_b32_e32 v80, v246
	v_mov_b32_e32 v81, v247
	v_mov_b32_e32 v120, v248
	v_mov_b32_e32 v121, v249
	v_mov_b32_e32 v122, v250
	v_mov_b32_e32 v123, v251
	s_nop 0
	v_mov_b32_e32 v64, v252
	v_mov_b32_e32 v65, v253
	v_mov_b32_e32 v66, v254
	v_mov_b32_e32 v67, v255
	v_mov_b32_e32 v127, v101
	v_mov_b32_e32 v112, v100
	v_mov_b32_e32 v126, v98
	v_mov_b32_e32 v125, v99
	v_mov_b32_e32 v124, v96
	v_mov_b32_e32 v82, v158
	v_mov_b32_e32 v83, v97
	v_mov_b32_e32 v116, v140
	v_mov_b32_e32 v117, v159
	v_mov_b32_e32 v113, v111
	v_mov_b32_e32 v106, v150
	v_mov_b32_e32 v107, v95
	v_mov_b32_e32 v114, v148
	v_mov_b32_e32 v115, v109
	v_mov_b32_e32 v104, v152
	v_mov_b32_e32 v105, v143
	s_waitcnt vmcnt(3)
	v_mov_b32_e32 v135, v70
	s_waitcnt vmcnt(0)
	v_mov_b32_e32 v128, v65
	v_mov_b32_e32 v129, v67
	v_mov_b32_e32 v118, v64
	v_mov_b32_e32 v119, v66
	v_pk_mul_f32 v[100:101], v[100:101], v[128:129]
	v_mov_b32_e32 v128, v74
	v_pk_fma_f32 v[118:119], v[154:155], v[118:119], v[100:101]
	v_mov_b32_e32 v101, v66
	v_mov_b32_e32 v129, v155
	v_mov_b32_e32 v66, v121
	v_mov_b32_e32 v100, v120
	v_pk_mul_f32 v[66:67], v[128:129], v[66:67]
	v_mov_b32_e32 v155, v93
	v_pk_fma_f32 v[100:101], v[126:127], v[100:101], v[66:67] neg_lo:[0,0,1] neg_hi:[0,0,1]
	v_mov_b32_e32 v66, v120
	v_mov_b32_e32 v120, v121
	v_mov_b32_e32 v121, v123
	v_mov_b32_e32 v67, v122
	v_pk_mul_f32 v[98:99], v[98:99], v[120:121]
	v_mov_b32_e32 v122, v79
	v_pk_fma_f32 v[120:121], v[74:75], v[66:67], v[98:99]
	v_mov_b32_e32 v74, v72
	v_mov_b32_e32 v66, v78
	v_pk_mul_f32 v[74:75], v[74:75], v[122:123]
	s_nop 0
	v_pk_fma_f32 v[98:99], v[124:125], v[66:67], v[74:75] neg_lo:[0,0,1] neg_hi:[0,0,1]
	v_mov_b32_e32 v74, v79
	v_mov_b32_e32 v75, v81
	v_mov_b32_e32 v67, v80
	v_pk_mul_f32 v[74:75], v[96:97], v[74:75]
	v_mov_b32_e32 v80, v69
	v_pk_fma_f32 v[122:123], v[72:73], v[66:67], v[74:75]
	v_mov_b32_e32 v72, v156
	v_mov_b32_e32 v66, v68
	v_pk_mul_f32 v[72:73], v[72:73], v[80:81]
	v_mov_b32_e32 v68, v69
	v_mov_b32_e32 v69, v71
	v_pk_fma_f32 v[96:97], v[82:83], v[66:67], v[72:73] neg_lo:[0,0,1] neg_hi:[0,0,1]
	v_mov_b32_e32 v67, v70
	v_pk_mul_f32 v[68:69], v[158:159], v[68:69]
	s_nop 0
	v_pk_fma_f32 v[124:125], v[156:157], v[66:67], v[68:69]
	v_lshlrev_b32_e32 v66, 7, v144
	v_and_b32_e32 v164, 0x1f80, v66
	v_lshl_add_u64 v[80:81], v[76:77], 0, v[164:165]
	global_load_dwordx4 v[66:69], v[80:81], off offset:48
	global_load_dwordx4 v[72:75], v[80:81], off offset:32
	global_load_dwordx4 v[76:79], v[80:81], off offset:16
	s_nop 0
	global_load_dwordx4 v[80:83], v[80:81], off
	v_mov_b32_e32 v156, v86
	v_mov_b32_e32 v86, v92
	s_waitcnt vmcnt(3)
	v_mov_b32_e32 v126, v67
	s_waitcnt vmcnt(2)
	v_mov_b32_e32 v128, v73
	s_waitcnt vmcnt(1)
	v_mov_b32_e32 v130, v77
	s_waitcnt vmcnt(0)
	v_mov_b32_e32 v70, v81
	v_mov_b32_e32 v132, v81
	v_mov_b32_e32 v134, v80
	v_pk_mul_f32 v[70:71], v[156:157], v[70:71]
	v_mov_b32_e32 v81, v83
	v_mov_b32_e32 v133, v82
	v_pk_fma_f32 v[158:159], v[116:117], v[134:135], v[70:71] neg_lo:[0,0,1] neg_hi:[0,0,1]
	v_pk_mul_f32 v[70:71], v[108:109], v[80:81]
	v_mov_b32_e32 v81, v82
	v_mov_b32_e32 v82, v77
	v_mov_b32_e32 v77, v79
	v_mov_b32_e32 v131, v78
	v_mov_b32_e32 v80, v76
	v_pk_mul_f32 v[82:83], v[86:87], v[82:83]
	v_pk_fma_f32 v[86:87], v[140:141], v[132:133], v[70:71]
	v_pk_mul_f32 v[70:71], v[110:111], v[76:77]
	v_mov_b32_e32 v76, v65
	v_pk_mul_f32 v[76:77], v[154:155], v[76:77]
	v_mov_b32_e32 v65, v78
	v_pk_fma_f32 v[92:93], v[148:149], v[130:131], v[70:71]
	v_mov_b32_e32 v70, v73
	v_mov_b32_e32 v71, v75
	v_pk_fma_f32 v[110:111], v[112:113], v[64:65], v[76:77] neg_lo:[0,0,1] neg_hi:[0,0,1]
	v_mov_b32_e32 v64, v72
	v_mov_b32_e32 v65, v75
	v_pk_mul_f32 v[70:71], v[88:89], v[70:71]
	v_mov_b32_e32 v73, v74
	v_mov_b32_e32 v129, v74
	v_pk_mul_f32 v[64:65], v[94:95], v[64:65]
	v_pk_fma_f32 v[94:95], v[106:107], v[72:73], v[70:71] neg_lo:[0,0,1] neg_hi:[0,0,1]
	v_mov_b32_e32 v70, v67
	v_mov_b32_e32 v71, v69
	v_pk_fma_f32 v[88:89], v[150:151], v[128:129], v[64:65]
	v_mov_b32_e32 v64, v66
	v_mov_b32_e32 v65, v69
	v_pk_mul_f32 v[70:71], v[90:91], v[70:71]
	v_mov_b32_e32 v67, v68
	v_mov_b32_e32 v127, v68
	v_pk_fma_f32 v[108:109], v[114:115], v[80:81], v[82:83] neg_lo:[0,0,1] neg_hi:[0,0,1]
	v_pk_mul_f32 v[64:65], v[142:143], v[64:65]
	v_pk_fma_f32 v[142:143], v[104:105], v[66:67], v[70:71] neg_lo:[0,0,1] neg_hi:[0,0,1]
	v_pk_fma_f32 v[90:91], v[152:153], v[126:127], v[64:65]
	v_mov_b64_e32 v[156:157], v[124:125]
	v_mov_b64_e32 v[72:73], v[122:123]
	v_mov_b64_e32 v[74:75], v[120:121]
	v_mov_b64_e32 v[154:155], v[118:119]
	v_mov_b32_e32 v148, v108
	v_mov_b32_e32 v140, v158
	v_mov_b32_e32 v158, v96
	v_mov_b32_e32 v96, v98
	v_mov_b32_e32 v98, v100
	v_mov_b32_e32 v100, v110
	v_mov_b32_e32 v150, v94
	v_mov_b32_e32 v152, v142
